# v56 + scan step A2 list-scheduled by the sched tool (critical-path order, 3 spare VGPRs for renaming; model single-wave time -23 %)
# baseline (speedup 1.0000x reference)
.LBB0_565:
	v_cndmask_b32_e64 v8, 0, 1, s[34:35]
	v_cmp_ne_u32_e64 s[24:25], 1, v8
	s_andn2_b64 vcc, exec, s[34:35]
	s_cbranch_vccnz .LBB0_573
	ds_read_b128 v[20:23], v226 offset:1536
	ds_read_b64 v[36:37], v115 offset:56320
	ds_read_b64 v[38:39], v116 offset:56320
	ds_read2_b64 v[82:85], v229 offset1:4
	ds_read_b128 v[24:27], v226 offset:1792
	ds_read_b64 v[40:41], v227
	ds_read_b64 v[42:43], v228
	ds_read2_b64 v[158:161], v230 offset1:4
	ds_read_b128 v[28:31], v226 offset:1600
	ds_read_b128 v[32:35], v226 offset:1856
	ds_read2st64_b32 v[248:249], v239 offset1:1
	ds_read2_b64 v[162:165], v238 offset1:4
	s_add_i32 s38, 0, 0x14800
	v_lshlrev_b32_e32 v9, 2, v240
	v_or_b32_e32 v157, 60, v9
	s_waitcnt lgkmcnt(8)
	v_mfma_f32_16x16x32_f16 v[20:23], v[82:85], v[36:39], v[20:23]
	ds_read2_b64 v[82:85], v231 offset1:4
	s_waitcnt lgkmcnt(5)
	v_mfma_f32_16x16x32_f16 v[24:27], v[158:161], v[40:43], v[24:27]
	ds_read2_b64 v[158:161], v232 offset1:4
	s_waitcnt lgkmcnt(3)
	v_add_f32_e32 v8, v248, v249
	v_max_f32_e32 v8, 0x179abe15, v8
	v_rsq_f32_e32 v8, v8
	s_waitcnt lgkmcnt(1)
	v_mfma_f32_16x16x32_f16 v[28:31], v[82:85], v[36:39], v[28:31]
	ds_read_b64 v[36:37], v119 offset:56320
	ds_read_b64 v[38:39], v120 offset:56320
	ds_read2_b64 v[82:85], v235 offset1:4
	s_waitcnt lgkmcnt(3)
	v_mfma_f32_16x16x32_f16 v[32:35], v[158:161], v[40:43], v[32:35]
	ds_read_b64 v[40:41], v233
	ds_read_b64 v[42:43], v234
	ds_read2_b64 v[158:161], v236 offset1:4
	s_waitcnt lgkmcnt(3)
	v_mfma_f32_16x16x32_f16 v[82:85], v[82:85], v[36:39], v[20:23]
	s_nop 2
	ds_read2_b64 v[20:23], v237 offset1:4
	s_waitcnt lgkmcnt(1)
	v_mfma_f32_16x16x32_f16 v[158:161], v[158:161], v[40:43], v[24:27]
	s_nop 1
	v_exp_f32_e32 v254, v82
	s_nop 0
	v_fmamk_f32 v248, v254, 0xbf92477c, v147
	v_rcp_f32_e32 v254, v248
	v_add_u32_e32 v248, s38, v123
	s_waitcnt lgkmcnt(0)
	v_mfma_f32_16x16x32_f16 v[24:27], v[20:23], v[36:39], v[28:31]
	v_exp_f32_e32 v37, v158
	v_mfma_f32_16x16x32_f16 v[20:23], v[162:165], v[40:43], v[32:35]
	v_add_f32_e32 v249, 1.0, v37
	ds_read_b128 v[28:31], v248 offset:1280
	v_rcp_f32_e32 v86, v249
	v_add_f32_dpp v249, v254, v254 row_shr:1 row_mask:0xf bank_mask:0xf bound_ctrl:1
	ds_read_b128 v[32:35], v248 offset:4864
	s_nop 0
	v_add_f32_dpp v37, v249, v249 row_shr:2 row_mask:0xf bank_mask:0xf bound_ctrl:1
	s_nop 1
	v_add_f32_dpp v249, v37, v37 row_shr:4 row_mask:0xf bank_mask:0xf bound_ctrl:1
	s_nop 1
	v_add_f32_dpp v248, v249, v249 row_shr:8 row_mask:0xf bank_mask:0xf bound_ctrl:1
	v_exp_f32_e32 v249, v159
	v_sub_f32_e32 v162, v248, v254
	v_exp_f32_e32 v254, v83
	v_add_f32_e32 v37, 1.0, v249
	ds_bpermute_b32 v40, v9, v248 offset:28
	v_fmamk_f32 v36, v254, 0xbf92477c, v147
	v_rcp_f32_e32 v87, v37
	v_rcp_f32_e32 v254, v36
	s_nop 2
	v_add_f32_dpp v249, v254, v254 row_shr:1 row_mask:0xf bank_mask:0xf bound_ctrl:1
	s_nop 1
	v_add_f32_dpp v37, v249, v249 row_shr:2 row_mask:0xf bank_mask:0xf bound_ctrl:1
	s_nop 1
	v_add_f32_dpp v249, v37, v37 row_shr:4 row_mask:0xf bank_mask:0xf bound_ctrl:1
	v_exp_f32_e32 v37, v160
	s_nop 0
	v_add_f32_dpp v83, v249, v249 row_shr:8 row_mask:0xf bank_mask:0xf bound_ctrl:1
	s_waitcnt lgkmcnt(1)
	v_pk_fma_f32 v[28:29], v[86:87], v[28:29], v[32:33]
	v_sub_f32_e32 v249, v83, v254
	v_exp_f32_e32 v254, v84
	v_add_f32_e32 v37, 1.0, v37
	ds_bpermute_b32 v41, v9, v83 offset:28
	v_fmamk_f32 v36, v254, 0xbf92477c, v147
	v_rcp_f32_e32 v158, v37
	v_rcp_f32_e32 v254, v36
	v_fma_mix_f32 v82, v66, v28, 0 op_sel_hi:[1,0,0]
	s_nop 1
	v_add_f32_dpp v37, v254, v254 row_shr:1 row_mask:0xf bank_mask:0xf bound_ctrl:1
	s_waitcnt lgkmcnt(1)
	v_sub_f32_e32 v84, v162, v40
	v_add_f32_dpp v37, v37, v37 row_shr:2 row_mask:0xf bank_mask:0xf bound_ctrl:1
	v_exp_f32_e32 v160, v84
	s_nop 0
	v_add_f32_dpp v37, v37, v37 row_shr:4 row_mask:0xf bank_mask:0xf bound_ctrl:1
	s_nop 1
	v_add_f32_dpp v166, v37, v37 row_shr:8 row_mask:0xf bank_mask:0xf bound_ctrl:1
	v_exp_f32_e32 v37, v161
	v_sub_f32_e32 v167, v166, v254
	v_exp_f32_e32 v254, v85
	v_add_f32_e32 v37, 1.0, v37
	ds_bpermute_b32 v42, v9, v166 offset:28
	v_fmamk_f32 v36, v254, 0xbf92477c, v147
	v_rcp_f32_e32 v159, v37
	v_rcp_f32_e32 v254, v36
	ds_bpermute_b32 v36, v157, v248
	ds_bpermute_b32 v38, v157, v166
	s_nop 0
	v_add_f32_dpp v37, v254, v254 row_shr:1 row_mask:0xf bank_mask:0xf bound_ctrl:1
	v_pk_fma_f32 v[30:31], v[158:159], v[30:31], v[34:35]
	s_nop 0
	v_add_f32_dpp v37, v37, v37 row_shr:2 row_mask:0xf bank_mask:0xf bound_ctrl:1
	v_fma_mix_f32 v84, v67, v30, 0 op_sel_hi:[1,0,0]
	v_fma_mix_f32 v85, v67, v31, 0 op_sel:[1,0,0] op_sel_hi:[1,0,0]
	v_add_f32_dpp v37, v37, v37 row_shr:4 row_mask:0xf bank_mask:0xf bound_ctrl:1
	v_fma_mix_f32 v30, v69, v8, 0 op_sel_hi:[1,0,0]
	v_fma_mix_f32 v31, v69, v8, 0 op_sel:[1,0,0] op_sel_hi:[1,0,0]
	v_add_f32_dpp v169, v37, v37 row_shr:8 row_mask:0xf bank_mask:0xf bound_ctrl:1
	ds_bpermute_b32 v37, v157, v83
	ds_bpermute_b32 v43, v9, v169 offset:28
	v_sub_f32_e32 v170, v169, v254
	v_sub_f32_e32 v254, v248, v40
	ds_bpermute_b32 v39, v157, v169
	v_exp_f32_e32 v248, v254
	s_waitcnt lgkmcnt(6)
	v_sub_f32_e32 v254, v249, v41
	v_exp_f32_e32 v161, v254
	v_sub_f32_e32 v254, v83, v41
	s_waitcnt lgkmcnt(5)
	v_sub_f32_e32 v33, v166, v42
	v_exp_f32_e32 v249, v254
	v_sub_f32_e32 v32, v167, v42
	v_exp_f32_e32 v166, v33
	v_rcp_f32_e32 v163, v249
	v_fma_mix_f32 v165, v74, v249, 0 op_sel:[1,0,0] op_sel_hi:[1,0,0]
	v_exp_f32_e32 v32, v32
	v_rcp_f32_e32 v168, v166
	v_rcp_f32_e32 v162, v248
	v_fma_mix_f32 v164, v74, v248, 0 op_sel_hi:[1,0,0]
	v_fma_mix_f32 v248, v68, v8, 0 op_sel_hi:[1,0,0]
	v_fma_mix_f32 v83, v66, v29, 0 op_sel:[1,0,0] op_sel_hi:[1,0,0]
	v_fma_mix_f32 v166, v75, v166, 0 op_sel_hi:[1,0,0]
	s_waitcnt lgkmcnt(1)
	v_sub_f32_e32 v249, v169, v43
	v_exp_f32_e32 v167, v249
	v_sub_f32_e32 v249, v170, v43
	v_exp_f32_e32 v33, v249
	v_rcp_f32_e32 v169, v167
	v_fma_mix_f32 v249, v68, v8, 0 op_sel:[1,0,0] op_sel_hi:[1,0,0]
	v_pk_mul_f32 v[32:33], v[30:31], v[32:33]
	v_pk_mul_f32 v[34:35], v[248:249], v[160:161]
	v_pk_mul_f32 v[28:29], v[86:87], v[248:249]
	v_pk_mul_f32 v[248:249], v[158:159], v[30:31]
	v_fma_mix_f32 v167, v75, v167, 0 op_sel:[1,0,0] op_sel_hi:[1,0,0]
	v_pk_mul_f32 v[30:31], v[248:249], v[168:169]
	v_pk_mul_f32 v[28:29], v[28:29], v[162:163]
	v_pk_mul_f32 v[86:87], v[82:83], v[162:163]
	v_pk_mul_f32 v[158:159], v[84:85], v[168:169]
	v_cvt_pk_f16_f32 v249, v32, v33
	v_cvt_pk_f16_f32 v248, v34, v35
	v_cvt_pk_f16_f32 v33, v166, v167
	v_cvt_pk_f16_f32 v32, v164, v165
	v_cvt_pk_f16_f32 v31, v30, v31
	v_cvt_pk_f16_f32 v30, v28, v29
	v_cvt_pk_f16_f32 v29, v158, v159
	v_cvt_pk_f16_f32 v28, v86, v87
	ds_write_b64 v214, v[248:249]
	ds_write_b64 v214, v[32:33] offset:2304
	ds_write_b64 v214, v[30:31] offset:4608
	ds_write_b64 v214, v[28:29] offset:6912
	s_waitcnt lgkmcnt(4)
	s_and_saveexec_b64 s[34:35], s[4:5]
	s_cbranch_execz .LBB0_568
	v_add_u32_e32 v28, s71, v123
	ds_write_b128 v28, v[40:43] offset:13568
	s_waitcnt lgkmcnt(0)
	ds_write_b128 v28, v[36:39] offset:13824
.LBB0_568:
	s_or_b64 exec, exec, s[34:35]
	v_exp_f32_e32 v248, v24
	v_exp_f32_e32 v254, v20
	v_exp_f32_e32 v249, v21
	v_fmamk_f32 v24, v248, 0xbf92477c, v147
	v_add_f32_e32 v20, 1.0, v254
	v_rcp_f32_e32 v248, v24
	v_rcp_f32_e32 v36, v20
	v_add_f32_e32 v21, 1.0, v249
	s_nop 0
	v_add_f32_dpp v254, v248, v248 row_shr:1 row_mask:0xf bank_mask:0xf bound_ctrl:1
	v_rcp_f32_e32 v37, v21
	s_nop 0
	v_add_f32_dpp v20, v254, v254 row_shr:2 row_mask:0xf bank_mask:0xf bound_ctrl:1
	v_add_u32_e32 v32, s38, v124
	v_or_b32_e32 v40, 28, v9
	v_add_f32_dpp v254, v20, v20 row_shr:4 row_mask:0xf bank_mask:0xf bound_ctrl:1
	ds_read_b128 v[28:31], v32 offset:1280
	s_nop 0
	v_add_f32_dpp v249, v254, v254 row_shr:8 row_mask:0xf bank_mask:0xf bound_ctrl:1
	v_exp_f32_e32 v254, v25
	v_sub_f32_e32 v42, v249, v248
	ds_read_b128 v[32:35], v32 offset:4864
	v_fmamk_f32 v248, v254, 0xbf92477c, v147
	ds_bpermute_b32 v24, v40, v249
	v_rcp_f32_e32 v254, v248
	v_exp_f32_e32 v248, v26
	v_cvt_f32_f16_sdwa v161, v70 dst_sel:DWORD dst_unused:UNUSED_PAD src0_sel:WORD_1
	s_nop 0
	v_add_f32_dpp v21, v254, v254 row_shr:1 row_mask:0xf bank_mask:0xf bound_ctrl:1
	v_cvt_f32_f16_e32 v160, v70
	v_mov_b32_e32 v9, v8
	v_add_f32_dpp v21, v21, v21 row_shr:2 row_mask:0xf bank_mask:0xf bound_ctrl:1
	v_cvt_f32_f16_sdwa v159, v78 dst_sel:DWORD dst_unused:UNUSED_PAD src0_sel:WORD_1
	v_cvt_f32_f16_e32 v158, v78
	v_add_f32_dpp v21, v21, v21 row_shr:4 row_mask:0xf bank_mask:0xf bound_ctrl:1
	s_nop 1
	v_add_f32_dpp v43, v21, v21 row_shr:8 row_mask:0xf bank_mask:0xf bound_ctrl:1
	v_exp_f32_e32 v21, v22
	v_sub_f32_e32 v87, v43, v254
	v_fmamk_f32 v254, v248, 0xbf92477c, v147
	ds_bpermute_b32 v25, v40, v43
	v_rcp_f32_e32 v248, v254
	v_add_f32_e32 v21, 1.0, v21
	v_rcp_f32_e32 v38, v21
	s_nop 0
	v_add_f32_dpp v21, v248, v248 row_shr:1 row_mask:0xf bank_mask:0xf bound_ctrl:1
	s_nop 1
	v_add_f32_dpp v21, v21, v21 row_shr:2 row_mask:0xf bank_mask:0xf bound_ctrl:1
	s_waitcnt lgkmcnt(2)
	v_pk_fma_f32 v[28:29], v[36:37], v[28:29], v[32:33]
	v_fma_mix_f32 v32, v72, v8, 0 op_sel_hi:[1,0,0]
	v_add_f32_dpp v21, v21, v21 row_shr:4 row_mask:0xf bank_mask:0xf bound_ctrl:1
	v_pk_fma_f32 v[28:29], v[160:161], v[28:29], 0 op_sel_hi:[1,1,0]
	s_waitcnt lgkmcnt(1)
	v_sub_f32_e32 v41, v249, v24
	v_add_f32_dpp v254, v21, v21 row_shr:8 row_mask:0xf bank_mask:0xf bound_ctrl:1
	v_exp_f32_e32 v21, v23
	v_sub_f32_e32 v163, v254, v248
	v_exp_f32_e32 v248, v27
	v_add_f32_e32 v21, 1.0, v21
	ds_bpermute_b32 v26, v40, v254
	v_fmamk_f32 v20, v248, 0xbf92477c, v147
	v_rcp_f32_e32 v39, v21
	v_rcp_f32_e32 v248, v20
	ds_bpermute_b32 v22, v157, v254
	ds_bpermute_b32 v20, v157, v249
	s_nop 0
	v_add_f32_dpp v21, v248, v248 row_shr:1 row_mask:0xf bank_mask:0xf bound_ctrl:1
	s_waitcnt lgkmcnt(3)
	v_sub_f32_e32 v249, v43, v25
	v_pk_fma_f32 v[30:31], v[38:39], v[30:31], v[34:35]
	v_add_f32_dpp v21, v21, v21 row_shr:2 row_mask:0xf bank_mask:0xf bound_ctrl:1
	v_cvt_f32_f16_sdwa v35, v73 dst_sel:DWORD dst_unused:UNUSED_PAD src0_sel:WORD_1
	v_cvt_f32_f16_e32 v34, v73
	v_add_f32_dpp v21, v21, v21 row_shr:4 row_mask:0xf bank_mask:0xf bound_ctrl:1
	v_fma_mix_f32 v33, v72, v9, 0 op_sel:[1,0,0] op_sel_hi:[1,0,0]
	v_pk_fma_f32 v[8:9], v[34:35], v[8:9], 0 op_sel_hi:[1,1,0]
	v_add_f32_dpp v165, v21, v21 row_shr:8 row_mask:0xf bank_mask:0xf bound_ctrl:1
	ds_bpermute_b32 v21, v157, v43
	ds_bpermute_b32 v27, v40, v165
	ds_bpermute_b32 v23, v157, v165
	v_sub_f32_e32 v166, v165, v248
	v_sub_f32_e32 v248, v42, v24
	v_exp_f32_e32 v42, v41
	v_exp_f32_e32 v43, v249
	v_sub_f32_e32 v249, v87, v25
	v_exp_f32_e32 v40, v248
	s_waitcnt lgkmcnt(5)
	v_sub_f32_e32 v157, v163, v26
	v_exp_f32_e32 v41, v249
	v_exp_f32_e32 v160, v157
	v_sub_f32_e32 v157, v254, v26
	v_rcp_f32_e32 v86, v42
	v_exp_f32_e32 v162, v157
	v_rcp_f32_e32 v87, v43
	v_pk_mul_f32 v[248:249], v[32:33], v[40:41]
	v_rcp_f32_e32 v164, v162
	v_pk_mul_f32 v[32:33], v[36:37], v[32:33]
	v_fma_mix_f32 v30, v71, v30, 0 op_sel_hi:[1,0,0]
	v_pk_mul_f32 v[32:33], v[32:33], v[86:87]
	v_fma_mix_f32 v31, v71, v31, 0 op_sel:[1,0,0] op_sel_hi:[1,0,0]
	v_pk_fma_f32 v[42:43], v[158:159], v[42:43], 0 op_sel_hi:[1,1,0]
	v_pk_mul_f32 v[36:37], v[28:29], v[86:87]
	v_fma_mix_f32 v158, v79, v162, 0 op_sel_hi:[1,0,0]
	s_waitcnt lgkmcnt(1)
	v_sub_f32_e32 v157, v166, v27
	v_add_u32_e32 v86, s71, v114
	v_exp_f32_e32 v161, v157
	v_sub_f32_e32 v157, v165, v27
	v_cvt_pk_f16_f32 v34, v42, v43
	v_exp_f32_e32 v163, v157
	v_pk_mul_f32 v[40:41], v[8:9], v[160:161]
	v_pk_mul_f32 v[8:9], v[38:39], v[8:9]
	v_cvt_pk_f16_f32 v41, v40, v41
	v_rcp_f32_e32 v165, v163
	v_fma_mix_f32 v159, v79, v163, 0 op_sel:[1,0,0] op_sel_hi:[1,0,0]
	v_cvt_pk_f16_f32 v40, v248, v249
	v_cvt_pk_f16_f32 v35, v158, v159
	v_pk_mul_f32 v[8:9], v[8:9], v[164:165]
	v_pk_mul_f32 v[38:39], v[30:31], v[164:165]
	v_cvt_pk_f16_f32 v9, v8, v9
	v_cvt_pk_f16_f32 v8, v32, v33
	ds_write_b64 v86, v[8:9] offset:4608
	v_cvt_pk_f16_f32 v9, v38, v39
	v_cvt_pk_f16_f32 v8, v36, v37
	ds_write_b64 v86, v[40:41]
	ds_write_b64 v86, v[34:35] offset:2304
	ds_write_b64 v86, v[8:9] offset:6912
	s_waitcnt lgkmcnt(4)
	s_and_saveexec_b64 s[34:35], s[4:5]
	s_cbranch_execz .LBB0_570
	v_add_u32_e32 v8, s71, v124
	ds_write_b128 v8, v[24:27] offset:13568
	ds_write_b128 v8, v[20:23] offset:13824
